# P0 x-conversion loads carry the nt hint (read-once f32 input no longer displaces xb / weights from the caches)
# speedup vs baseline: 1.0202x; 1.0125x over previous
; DI u32x2 pk4(f32x4 v) { u32x2 r; r.x = pk2(v[0], v[1]); r.y = pk2(v[2], v[3]); return r; }
;     ...
;     for (int r0 = gw * 8; r0 < T_TOK; r0 += ngw * 8) {
;       f32x4 v[8][4];
; #pragma unroll
;       for (int rr = 0; rr < 8; ++rr) {
;         const f32x4* xr = (const f32x4*)(p.x + (long)(r0 + rr) * DM) + lane;
; #pragma unroll
;         for (int j = 0; j < 4; ++j) v[rr][j] = xr[64 * j];
;       }
; #pragma unroll
;       for (int rr = 0; rr < 8; ++rr) {
;         float s = 0.f;
; #pragma unroll
;         for (int j = 0; j < 4; ++j) s += v[rr][j][0] * v[rr][j][0] + v[rr][j][1] * v[rr][j][1] + v[rr][j][2] * v[rr][j][2] + v[rr][j][3] * v[rr][j][3];
; #pragma unroll
;         for (int o = 1; o < 64; o <<= 1) s += __shfl_xor(s, o);
;         if (lane == 0) { const float rv = 1.0f / sqrtf(s * (1.0f / DM) + 1e-6f); const int r = r0 + rr, rl = r & 255;
;           rstd1[r] = rv; ((float*)(ws + OFF_RSTD1Q))[(r & ~255) + (((rl >> 6) & 1) * 16 + (rl & 15)) * 8 + (rl >> 7) * 4 + ((rl >> 4) & 3)] = rv; }
;         u32x2* o8 = (u32x2*)(xb + (long)(r0 + rr) * DM) + lane;
; #pragma unroll
;         for (int j = 0; j < 4; ++j) o8[64 * j] = pk4(v[rr][j]);
;       }
.LBB0_8:
	v_add_co_u32_e32 v2, vcc, 0xffff9000, v136
	v_lshrrev_b32_e32 v152, 2, v130
	s_nop 0
	v_addc_co_u32_e32 v3, vcc, -1, v137, vcc
	global_load_dwordx4 v[126:129], v[2:3], off offset:-3072 nt
	global_load_dwordx4 v[122:125], v[2:3], off offset:-2048 nt
	global_load_dwordx4 v[118:121], v[2:3], off offset:-1024 nt
	global_load_dwordx4 v[114:117], v[2:3], off nt
	v_add_co_u32_e32 v2, vcc, 0xffffa000, v136
	v_lshrrev_b32_e32 v153, 5, v130
	s_nop 0
	v_addc_co_u32_e32 v3, vcc, -1, v137, vcc
	v_add_co_u32_e32 v4, vcc, 0xffffb000, v136
	global_load_dwordx4 v[102:105], v[2:3], off offset:-3072 nt
	global_load_dwordx4 v[98:101], v[2:3], off offset:-2048 nt
	global_load_dwordx4 v[110:113], v[2:3], off offset:-1024 nt
	global_load_dwordx4 v[106:109], v[2:3], off nt
	v_addc_co_u32_e32 v5, vcc, -1, v137, vcc
	v_add_co_u32_e32 v2, vcc, 0xffffc000, v136
	v_and_b32_e32 v151, 0xffffff00, v130
	s_nop 0
	v_addc_co_u32_e32 v3, vcc, -1, v137, vcc
	v_add_co_u32_e32 v6, vcc, 0xffffd000, v136
	s_waitcnt vmcnt(7)
	v_mul_f32_e32 v147, v127, v127
	v_addc_co_u32_e32 v7, vcc, -1, v137, vcc
	v_add_co_u32_e32 v8, vcc, 0xffffe000, v136
	s_waitcnt vmcnt(6)
	v_mul_f32_e32 v148, v123, v123
	v_addc_co_u32_e32 v9, vcc, -1, v137, vcc
	v_add_co_u32_e32 v22, vcc, 0xfffff000, v136
	s_waitcnt vmcnt(5)
	v_mul_f32_e32 v149, v119, v119
	v_addc_co_u32_e32 v23, vcc, -1, v137, vcc
	global_load_dwordx4 v[94:97], v[4:5], off offset:-3072 nt
	global_load_dwordx4 v[90:93], v[4:5], off offset:-2048 nt
	global_load_dwordx4 v[86:89], v[4:5], off offset:-1024 nt
	global_load_dwordx4 v[82:85], v[4:5], off nt
	global_load_dwordx4 v[78:81], v[2:3], off offset:-3072 nt
	global_load_dwordx4 v[74:77], v[2:3], off offset:-2048 nt
	global_load_dwordx4 v[70:73], v[2:3], off offset:-1024 nt
	global_load_dwordx4 v[66:69], v[2:3], off nt
	global_load_dwordx4 v[62:65], v[6:7], off offset:-3072 nt
	global_load_dwordx4 v[58:61], v[6:7], off offset:-2048 nt
	global_load_dwordx4 v[54:57], v[6:7], off offset:-1024 nt
	global_load_dwordx4 v[50:53], v[6:7], off nt
	global_load_dwordx4 v[46:49], v[8:9], off offset:-3072 nt
	global_load_dwordx4 v[42:45], v[8:9], off offset:-2048 nt
	global_load_dwordx4 v[38:41], v[8:9], off offset:-1024 nt
	global_load_dwordx4 v[34:37], v[8:9], off nt
	global_load_dwordx4 v[26:29], v[22:23], off offset:-3072 nt
	s_waitcnt lgkmcnt(0)
	global_load_dwordx4 v[18:21], v[22:23], off offset:-2048 nt
	global_load_dwordx4 v[14:17], v[136:137], off offset:-3072 nt
	global_load_dwordx4 v[10:13], v[136:137], off offset:-2048 nt
	global_load_dwordx4 v[6:9], v[136:137], off offset:-1024 nt
	global_load_dwordx4 v[2:5], v[136:137], off nt
	global_load_dwordx4 v[30:33], v[22:23], off offset:-1024 nt
	s_nop 0
	global_load_dwordx4 v[22:25], v[136:137], off offset:-4096 nt
	v_fmac_f32_e32 v147, v126, v126
	v_fmac_f32_e32 v148, v122, v122
	s_waitcnt vmcnt(28)
	v_mul_f32_e32 v150, v115, v115
	v_fmac_f32_e32 v149, v118, v118
	v_fmac_f32_e32 v147, v128, v128
	v_fmac_f32_e32 v148, v124, v124
	v_fmac_f32_e32 v150, v114, v114
	v_fmac_f32_e32 v149, v120, v120
	v_fmac_f32_e32 v147, v129, v129
	v_fmac_f32_e32 v148, v125, v125
	v_fmac_f32_e32 v150, v116, v116
	v_fmac_f32_e32 v149, v121, v121
	v_add_f32_e32 v147, v147, v148
	v_fmac_f32_e32 v150, v117, v117
	v_add_f32_e32 v147, v147, v149
	v_add_f32_e32 v147, v147, v150
	ds_bpermute_b32 v148, v1, v147
	s_waitcnt lgkmcnt(0)
	v_add_f32_e32 v147, v147, v148
	ds_bpermute_b32 v148, v141, v147
	s_waitcnt lgkmcnt(0)
	v_add_f32_e32 v147, v147, v148
	ds_bpermute_b32 v148, v142, v147
	s_waitcnt lgkmcnt(0)
	v_add_f32_e32 v147, v147, v148
	ds_bpermute_b32 v148, v143, v147
	s_waitcnt lgkmcnt(0)
	v_add_f32_e32 v147, v147, v148
	ds_bpermute_b32 v148, v144, v147
	s_waitcnt lgkmcnt(0)
	v_add_f32_e32 v149, v147, v148
	ds_bpermute_b32 v150, v145, v149
	v_bfe_u32 v148, v130, 4, 2
	v_and_b32_e32 v147, 16, v152
	v_and_b32_e32 v152, 4, v153
	v_or3_b32 v148, v152, v151, v148
	s_and_saveexec_b64 s[58:59], s[4:5]
	s_cbranch_execz .LBB0_10
	s_waitcnt lgkmcnt(0)
	v_add_f32_e32 v149, v149, v150
	v_fmamk_f32 v149, v149, 0x3a800000, v131
	v_mul_f32_e32 v150, 0x4f800000, v149
	v_cmp_gt_f32_e32 vcc, s3, v149
	s_nop 1
	v_cndmask_b32_e32 v149, v149, v150, vcc
	v_sqrt_f32_e32 v150, v149
	s_nop 0
	v_add_u32_e32 v151, -1, v150
	v_fma_f32 v153, -v151, v150, v149
	v_add_u32_e32 v152, 1, v150
	v_cmp_ge_f32_e64 s[0:1], 0, v153
	s_nop 1
	v_cndmask_b32_e64 v151, v150, v151, s[0:1]
	v_fma_f32 v150, -v152, v150, v149
	v_cmp_lt_f32_e64 s[0:1], 0, v150
	s_nop 1
	v_cndmask_b32_e64 v150, v151, v152, s[0:1]
	v_mul_f32_e32 v151, 0x37800000, v150
	v_cndmask_b32_e32 v150, v150, v151, vcc
	v_cmp_class_f32_e32 vcc, v149, v146
	s_nop 1
	v_cndmask_b32_e32 v149, v150, v149, vcc
	v_div_scale_f32 v150, s[0:1], v149, v149, 1.0
	v_rcp_f32_e32 v151, v150
	s_nop 0
	v_fma_f32 v152, -v150, v151, 1.0
	v_fmac_f32_e32 v151, v152, v151
	v_div_scale_f32 v152, vcc, 1.0, v149, 1.0
	v_mul_f32_e32 v153, v152, v151
	v_fma_f32 v154, -v150, v153, v152
	v_fmac_f32_e32 v153, v154, v151
	v_fma_f32 v150, -v150, v153, v152
	v_div_fmas_f32 v150, v150, v151, v153
	v_div_fixup_f32 v149, v150, v149, 1.0
	v_and_or_b32 v150, v130, 8, v147
	v_lshl_or_b32 v150, v150, 3, v148
	v_ashrrev_i32_e32 v151, 31, v150
	v_lshl_add_u64 v[150:151], v[150:151], 2, s[20:21]
	global_store_dword v[132:133], v149, off offset:-28
	global_store_dword v[150:151], v149, off
